# P7 prep: non-temporal (nt) hint on the output stores
# baseline (speedup 1.0000x reference)
.LBB0_77:
	s_or_b64 exec, exec, s[36:37]
	v_mov_b32_e32 v76, v64
	v_mov_b32_e32 v77, v52
	v_mov_b32_e32 v78, v65
	v_mov_b32_e32 v79, v53
	v_mov_b32_e32 v80, v62
	v_mov_b32_e32 v81, v54
	v_mov_b32_e32 v82, v63
	v_mov_b32_e32 v83, v55
	v_mov_b32_e32 v84, v60
	v_mov_b32_e32 v85, v56
	v_mov_b32_e32 v86, v61
	v_mov_b32_e32 v87, v57
	v_mov_b32_e32 v88, v50
	v_mov_b32_e32 v89, v58
	v_mov_b32_e32 v90, v51
	v_mov_b32_e32 v91, v59
	v_pk_mul_f32 v[76:77], v[38:39], v[76:77]
	v_pk_mul_f32 v[78:79], v[4:5], v[78:79]
	v_pk_mul_f32 v[80:81], v[34:35], v[80:81]
	v_pk_mul_f32 v[82:83], v[6:7], v[82:83]
	v_ashrrev_i32_e32 v67, 31, v66
	v_pk_mul_f32 v[84:85], v[32:33], v[84:85]
	v_pk_mul_f32 v[86:87], v[0:1], v[86:87]
	v_pk_mul_f32 v[88:89], v[30:31], v[88:89]
	v_pk_mul_f32 v[90:91], v[2:3], v[90:91]
	v_fma_f32 v71, v8, v40, v76
	v_fma_f32 v76, v9, v41, v78
	v_fma_f32 v78, v10, v42, v80
	v_fma_f32 v80, v11, v43, v82
	v_lshlrev_b64 v[66:67], 11, v[66:67]
	v_fma_f32 v82, v16, v44, v84
	v_fma_f32 v84, v17, v45, v86
	v_fma_f32 v86, v18, v46, v88
	v_fma_f32 v88, v19, v47, v90
	v_mov_b64_e32 v[42:43], v[62:63]
	v_mov_b64_e32 v[44:45], v[60:61]
	v_add_f32_e32 v60, v71, v77
	v_add_f32_e32 v61, v76, v79
	v_add_f32_e32 v62, v78, v81
	v_add_f32_e32 v63, v80, v83
	v_lshl_add_u64 v[46:47], v[26:27], 0, v[66:67]
	v_mov_b64_e32 v[40:41], v[64:65]
	v_add_f32_e32 v64, v82, v85
	v_add_f32_e32 v65, v84, v87
	v_add_f32_e32 v66, v86, v89
	v_add_f32_e32 v67, v88, v91
	v_add_f32_e32 v60, v12, v60
	v_add_f32_e32 v61, v13, v61
	v_add_f32_e32 v62, v14, v62
	v_add_f32_e32 v63, v15, v63
	s_add_i32 s7, s7, 1
	v_add_f32_e32 v64, v20, v64
	v_add_f32_e32 v65, v21, v65
	v_add_f32_e32 v66, v22, v66
	v_add_f32_e32 v67, v23, v67
	s_cmp_eq_u32 s7, 16
	s_waitcnt vmcnt(0)
	v_lshlrev_b32_e32 v71, 16, v92
	v_and_b32_e32 v72, 0xffff0000, v92
	v_lshlrev_b32_e32 v76, 16, v93
	v_and_b32_e32 v73, 0xffff0000, v93
	v_lshlrev_b32_e32 v77, 16, v94
	v_and_b32_e32 v74, 0xffff0000, v94
	v_lshlrev_b32_e32 v78, 16, v95
	v_and_b32_e32 v75, 0xffff0000, v95
	v_mul_f32_e32 v60, v60, v71
	v_mul_f32_e32 v61, v61, v72
	v_mul_f32_e32 v62, v62, v76
	v_mul_f32_e32 v63, v63, v73
	v_mul_f32_e32 v64, v64, v77
	v_mul_f32_e32 v65, v65, v74
	v_mul_f32_e32 v66, v66, v78
	v_mul_f32_e32 v67, v67, v75
	v_cvt_pk_bf16_f32 v60, v60, v61
	v_cvt_pk_bf16_f32 v61, v62, v63
	v_cvt_pk_bf16_f32 v62, v64, v65
	v_cvt_pk_bf16_f32 v63, v66, v67
	global_store_dwordx4 v[46:47], v[60:63], off nt
	v_mov_b64_e32 v[46:47], v[50:51]
	s_cbranch_scc1 .LBB0_73

.LBB0_86:
	s_or_b64 exec, exec, s[36:37]
	v_add_f32_e32 v106, v106, v128
	v_fma_f32 v106, v106, 0.5, -v75
	v_add_f32_e32 v104, v104, v132
	v_add_f32_e32 v103, v103, v123
	v_fma_f32 v140, v28, v106, v75
	v_add_f32_e32 v106, v111, v120
	v_fma_f32 v104, v104, 0.5, -v76
	v_fma_f32 v103, v103, 0.5, -v81
	v_fma_f32 v106, v106, 0.5, -v79
	v_fma_f32 v142, v29, v104, v76
	v_add_f32_e32 v104, v107, v121
	v_fma_f32 v145, v6, v103, v81
	v_add_f32_e32 v103, v108, v126
	v_add_f32_e32 v102, v102, v129
	v_fma_f32 v111, v4, v106, v79
	v_add_f32_e32 v106, v118, v124
	v_fma_f32 v104, v104, 0.5, -v80
	v_fma_f32 v103, v103, 0.5, -v86
	v_add_f32_e32 v99, v99, v122
	v_fma_f32 v102, v102, 0.5, -v88
	v_fma_f32 v106, v106, 0.5, -v84
	v_mul_f32_e32 v141, v20, v111
	v_fma_f32 v143, v5, v104, v80
	v_fma_f32 v108, v10, v103, v86
	v_fma_f32 v99, v99, 0.5, -v82
	v_add_f32_e32 v103, v119, v37
	v_pk_add_f32 v[58:59], v[58:59], v[60:61]
	v_fma_f32 v149, v12, v102, v88
	v_add_f32_e32 v102, v109, v51
	v_fma_f32 v118, v8, v106, v84
	v_mul_f32_e32 v106, v141, v141
	v_mul_f32_e32 v144, v21, v143
	v_fma_f32 v147, v7, v99, v82
	v_add_f32_e32 v99, v105, v127
	v_fma_f32 v103, v103, 0.5, -v117
	v_fma_f32 v102, v102, 0.5, -v116
	v_pk_fma_f32 v[58:59], v[58:59], 0.5, v[52:53] op_sel_hi:[1,0,1] neg_lo:[0,0,1] neg_hi:[0,0,1]
	v_add_f32_e32 v104, v113, v125
	v_fmac_f32_e32 v106, v144, v144
	v_mul_f32_e32 v146, v22, v145
	v_fma_f32 v99, v99, 0.5, -v87
	v_fma_f32 v119, v0, v103, v117
	v_fma_f32 v109, v1, v102, v116
	v_pk_fma_f32 v[102:103], v[16:17], v[58:59], v[52:53]
	v_fma_f32 v104, v104, 0.5, -v85
	v_fmac_f32_e32 v106, v146, v146
	v_fma_f32 v148, v11, v99, v87
	v_mul_f32_e32 v99, v23, v147
	v_pk_mul_f32 v[58:59], v[24:25], v[102:103]
	v_fma_f32 v113, v9, v104, v85
	v_fmac_f32_e32 v106, v99, v99
	v_pk_mul_f32 v[104:105], v[58:59], v[58:59]
	v_pk_add_f32 v[56:57], v[56:57], v[62:63]
	v_add_f32_e32 v104, v104, v106
	v_pk_fma_f32 v[56:57], v[56:57], 0.5, v[54:55] op_sel_hi:[1,0,1] neg_lo:[0,0,1] neg_hi:[0,0,1]
	v_add_f32_e32 v150, v105, v104
	v_pk_fma_f32 v[104:105], v[18:19], v[56:57], v[54:55]
	v_add_f32_e32 v98, v98, v112
	v_pk_mul_f32 v[56:57], v[26:27], v[104:105]
	v_add_f32_e32 v65, v65, v133
	v_pk_mul_f32 v[106:107], v[56:57], v[56:57]
	v_add_f32_e32 v100, v100, v136
	v_add_f32_e32 v106, v106, v150
	v_add_f32_e32 v106, v107, v106
	ds_bpermute_b32 v107, v39, v106
	v_add_f32_e32 v97, v97, v139
	v_add_f32_e32 v101, v101, v110
	v_fma_f32 v98, v98, 0.5, -v114
	v_fma_f32 v65, v65, 0.5, -v92
	s_waitcnt lgkmcnt(0)
	v_add_f32_e32 v106, v106, v107
	ds_bpermute_b32 v107, v66, v106
	v_fma_f32 v100, v100, 0.5, -v77
	v_fma_f32 v97, v97, 0.5, -v78
	v_fma_f32 v101, v101, 0.5, -v115
	v_fma_f32 v98, v3, v98, v114
	s_waitcnt lgkmcnt(0)
	v_add_f32_e32 v106, v106, v107
	ds_bpermute_b32 v107, v67, v106
	v_fma_f32 v100, v30, v100, v77
	v_fma_f32 v97, v31, v97, v78
	v_fma_f32 v101, v2, v101, v115
	v_add_f32_e32 v91, v91, v130
	s_waitcnt lgkmcnt(0)
	v_add_f32_e32 v106, v106, v107
	v_add_f32_e32 v106, 0x2b8cbccc, v106
	v_rsq_f32_e32 v106, v106
	v_fma_f32 v107, v15, v65, v92
	v_ashrrev_i32_e32 v65, 31, v64
	v_fma_f32 v91, v91, 0.5, -v89
	v_mul_f32_e32 v141, v141, v106
	v_mul_f32_e32 v144, v144, v106
	v_mul_f32_e32 v146, v146, v106
	v_mul_f32_e32 v150, v99, v106
	v_mul_f32_e32 v151, v58, v106
	v_mul_f32_e32 v152, v59, v106
	v_mul_f32_e32 v153, v56, v106
	v_mul_f32_e32 v106, v57, v106
	v_cvt_pk_bf16_f32 v56, v140, v142
	v_cvt_pk_bf16_f32 v57, v100, v97
	v_cvt_pk_bf16_f32 v58, v119, v109
	v_cvt_pk_bf16_f32 v59, v101, v98
	v_lshlrev_b64 v[98:99], 9, v[64:65]
	v_lshlrev_b64 v[64:65], 10, v[64:65]
	v_lshl_add_u64 v[100:101], v[40:41], 0, v[64:65]
	v_add_f32_e32 v83, v83, v131
	global_store_dwordx4 v[100:101], v[56:59], off nt
	v_lshl_add_u64 v[100:101], v[42:43], 0, v[64:65]
	v_fma_f32 v91, v13, v91, v89
	v_cvt_pk_bf16_f32 v56, v111, v143
	v_cvt_pk_bf16_f32 v57, v145, v147
	v_cvt_pk_bf16_f32 v58, v102, v103
	v_fma_f32 v83, v83, 0.5, -v90
	v_cvt_pk_bf16_f32 v59, v104, v105
	global_store_dwordx4 v[100:101], v[56:59], off nt
	v_lshl_add_u64 v[100:101], v[44:45], 0, v[64:65]
	v_fma_f32 v83, v14, v83, v90
	v_cvt_pk_bf16_f32 v56, v118, v113
	v_cvt_pk_bf16_f32 v57, v108, v148
	v_cvt_pk_bf16_f32 v58, v149, v91
	v_cvt_pk_bf16_f32 v59, v83, v107
	global_store_dwordx4 v[100:101], v[56:59], off nt
	v_lshl_add_u64 v[64:65], v[46:47], 0, v[64:65]
	v_add_f32_e32 v73, v73, v134
	v_cvt_pk_bf16_f32 v56, v141, v144
	v_cvt_pk_bf16_f32 v57, v146, v150
	v_cvt_pk_bf16_f32 v58, v151, v152
	v_cvt_pk_bf16_f32 v59, v153, v106
	v_fma_f32 v73, v73, 0.5, -v93
	global_store_dwordx4 v[64:65], v[56:59], off nt
	v_fma_f32 v73, v32, v73, v93
	v_add_f32_e32 v83, v73, v73
	v_add_f32_e32 v58, v72, v135
	v_fma_f32 v58, v58, 0.5, -v94
	v_fma_f32 v58, v33, v58, v94
	v_mul_f32_e32 v83, 0xbfb8aa3b, v83
	v_mul_f32_e32 v91, 0xbfb8aa3b, v73
	v_add_f32_e32 v59, v58, v58
	v_exp_f32_e32 v83, v83
	v_exp_f32_e32 v91, v91
	v_mul_f32_e32 v59, 0xbfb8aa3b, v59
	v_exp_f32_e32 v59, v59
	v_mul_f32_e32 v64, 0xbfb8aa3b, v58
	v_add_f32_e32 v56, 1.0, v83
	v_add_f32_e32 v57, 1.0, v91
	v_exp_f32_e32 v64, v64
	v_rcp_f32_e32 v56, v56
	v_rcp_f32_e32 v57, v57
	v_add_f32_e32 v59, 1.0, v59
	v_rcp_f32_e32 v59, v59
	v_add_f32_e32 v64, 1.0, v64
	v_fma_f32 v56, v56, 2.0, -1.0
	v_rcp_f32_e32 v64, v64
	v_cndmask_b32_e64 v57, v57, v73, s[38:39]
	v_cndmask_b32_e32 v56, v57, v56, vcc
	v_fma_f32 v57, v59, 2.0, -1.0
	v_add_f32_e32 v59, v71, v137
	v_fma_f32 v59, v59, 0.5, -v95
	v_fma_f32 v59, v34, v59, v95
	v_cndmask_b32_e64 v58, v64, v58, s[38:39]
	v_add_f32_e32 v64, v59, v59
	v_mul_f32_e32 v64, 0xbfb8aa3b, v64
	v_mul_f32_e32 v65, 0xbfb8aa3b, v59
	v_exp_f32_e32 v64, v64
	v_exp_f32_e32 v65, v65
	v_cndmask_b32_e32 v57, v58, v57, vcc
	v_cvt_pk_bf16_f32 v56, v56, v57
	v_add_f32_e32 v58, 1.0, v64
	v_add_f32_e32 v64, 1.0, v65
	v_add_f32_e32 v65, v70, v138
	v_fma_f32 v65, v65, 0.5, -v96
	v_fma_f32 v65, v35, v65, v96
	v_add_f32_e32 v70, v65, v65
	v_mul_f32_e32 v70, 0xbfb8aa3b, v70
	v_mul_f32_e32 v71, 0xbfb8aa3b, v65
	v_exp_f32_e32 v70, v70
	v_exp_f32_e32 v71, v71
	v_rcp_f32_e32 v58, v58
	v_rcp_f32_e32 v64, v64
	v_add_f32_e32 v70, 1.0, v70
	v_add_f32_e32 v71, 1.0, v71
	v_rcp_f32_e32 v70, v70
	v_rcp_f32_e32 v71, v71
	v_fma_f32 v58, v58, 2.0, -1.0
	v_cndmask_b32_e64 v59, v64, v59, s[38:39]
	v_cndmask_b32_e32 v58, v59, v58, vcc
	v_fma_f32 v59, v70, 2.0, -1.0
	v_cndmask_b32_e64 v64, v71, v65, s[38:39]
	v_cndmask_b32_e32 v59, v64, v59, vcc
	v_cvt_pk_bf16_f32 v57, v58, v59
	v_lshl_add_u64 v[58:59], v[48:49], 0, v[98:99]
	s_add_i32 s6, s6, 1
	global_store_dwordx2 v[58:59], v[56:57], off nt
	s_cmp_eq_u32 s6, 16
	v_mov_b32_e32 v97, v78
	v_mov_b32_e32 v100, v77
	v_mov_b32_e32 v104, v76
	v_mov_b32_e32 v106, v75
	v_mov_b32_e32 v99, v82
	v_mov_b32_e32 v103, v81
	v_mov_b32_e32 v107, v80
	v_mov_b32_e32 v111, v79
	v_mov_b32_e32 v65, v92
	v_mov_b32_e32 v83, v90
	v_mov_b32_e32 v91, v89
	v_mov_b32_e32 v102, v88
	v_mov_b32_e32 v105, v87
	v_mov_b32_e32 v108, v86
	v_mov_b32_e32 v113, v85
	v_mov_b32_e32 v118, v84
	v_mov_b32_e32 v70, v96
	v_mov_b32_e32 v71, v95
	v_mov_b32_e32 v72, v94
	v_mov_b32_e32 v73, v93
	v_mov_b32_e32 v78, v139
	v_mov_b32_e32 v77, v136
	v_mov_b32_e32 v76, v132
	v_mov_b32_e32 v75, v128
	v_mov_b32_e32 v82, v122
	v_mov_b32_e32 v81, v123
	v_mov_b32_e32 v80, v121
	v_mov_b32_e32 v79, v120
	v_mov_b32_e32 v92, v133
	v_mov_b32_e32 v90, v131
	v_mov_b32_e32 v89, v130
	v_mov_b32_e32 v88, v129
	v_mov_b32_e32 v87, v127
	v_mov_b32_e32 v86, v126
	v_mov_b32_e32 v85, v125
	v_mov_b32_e32 v84, v124
	v_mov_b32_e32 v96, v138
	v_mov_b32_e32 v95, v137
	v_mov_b32_e32 v94, v135
	v_mov_b32_e32 v93, v134
	v_mov_b32_e32 v119, v117
	v_mov_b32_e32 v109, v116
	v_mov_b32_e32 v101, v115
	v_mov_b32_e32 v98, v114
	v_mov_b64_e32 v[56:57], v[54:55]
	v_mov_b64_e32 v[58:59], v[52:53]
	s_cbranch_scc1 .LBB0_82
